# x3 + merge GEMM chain epilogue: nine gate-code load round trips no longer waited for at the load (wait and copies deferred to first use)
# speedup vs baseline: 1.0070x; 1.0070x over previous
; __device__ __forceinline__ unsigned cvt_pk_bf16(float lo, float hi) { const f32x2_cv v = {lo, hi}; const bf16x2_cv b = __builtin_convertvector(v, bf16x2_cv); return __builtin_bit_cast(unsigned, b); }
; __device__ __forceinline__ float gate_c(unsigned w, int j) { return (float)((w >> (8 * j)) & 0xffu) + 0.5f; }
; __device__ __forceinline__ float gate_dq(unsigned w, int j) { return (float)((w >> (8 * j)) & 0xffu) * 0.00390625f + 0.001953125f; }
; #define MG_LOAD(k_, s_) do { const int ai_ = (k_) >> 3, m_ = ((k_) >> 1) & 3, bj_ = (k_) & 1; const unsigned char* q_ = gt + (size_t)(ai_ * HALF + m_ * 16) * 3072 + bj_ * HALF; \
;             ga[s_] = *(const v2u*)q_; gb[s_] = nb < 2 ? *(const v2u*)(q_ + 1024) : (v2u){0u, 0u}; } while (0)
;     __device__ __forceinline__ void operator()(f32x4 (&acc)[2][2][4][2], const Unit& u, int wr, int wc, int fr, int fq) const {
;     ...
; #pragma unroll
;         for (int k = 0; k < PD; ++k) MG_LOAD(k, k);
; #pragma unroll
;         for (int k = 0; k < 16; ++k) { const int ai = k >> 3, m = (k >> 1) & 3, bj = k & 1, s = k % PD;
;             const v2u gw = ga[s], hw = gb[s];
;             asm volatile("" :: "v"(gw), "v"(hw));
;             if (k + PD < 16) MG_LOAD(k + PD, s);
;             f32x4 o0 = acc[ai][bj][m][0], o1 = acc[ai][bj][m][1];
;             if (nb < 2) {
; #pragma unroll
;                 for (int j = 0; j < 4; ++j) { o0[j] *= gate_c(gw.x, j) * __builtin_amdgcn_rcpf(gate_c(hw.x, j)); o1[j] *= gate_c(gw.y, j) * __builtin_amdgcn_rcpf(gate_c(hw.y, j)); }
;                 acc[ai][bj][m][0] = o0; acc[ai][bj][m][1] = o1;
;             } else {
; #pragma unroll
;                 for (int j = 0; j < 4; ++j) { o0[j] *= gate_dq(gw.x, j); o1[j] *= gate_dq(gw.y, j); }
;                 u32x4 w; w.x = cvt_pk_bf16(o0[0], o0[1]); w.y = cvt_pk_bf16(o0[2], o0[3]); w.z = cvt_pk_bf16(o1[0], o1[1]); w.w = cvt_pk_bf16(o1[2], o1[3]);
;                 *(u32x4*)(MM + (size_t)(row0 + ai * HALF + m * 16) * 1024 + col0 + bj * HALF) = w;
.LBB0_1175:
	v_add_co_u32_e32 v144, vcc, 0x24000, v178
	s_waitcnt vmcnt(0)
	v_mov_b32_e32 v176, 0
	v_addc_co_u32_e32 v145, vcc, 0, v179, vcc
	global_load_dwordx2 v[172:173], v[144:145], off
	s_and_b64 vcc, exec, s[8:9]
	v_mov_b32_e32 v177, 0
	v_mov_b32_e32 v204, 0
	v_mov_b32_e32 v200, 0
	s_cbranch_vccnz .LBB0_1177
	v_add_co_u32_e32 v144, vcc, 0x24000, v178
	s_nop 1
	v_addc_co_u32_e32 v145, vcc, 0, v179, vcc
	global_load_dwordx2 v[176:177], v[144:145], off offset:1024
.LBB0_1177:
	v_ashrrev_i32_e32 v171, 31, v170
	v_cndmask_b32_e64 v144, 0, 1, s[26:27]
	v_or_b32_e32 v158, s6, v198
	v_cmp_ne_u32_e64 s[6:7], 1, v144
	v_lshlrev_b64 v[144:145], 11, v[170:171]
	v_ashrrev_i32_e32 v159, 31, v158
	v_cvt_f32_ubyte0_e32 v190, v142
	s_mov_b64 s[28:29], -1
	s_andn2_b64 vcc, exec, s[26:27]
	v_cvt_f32_ubyte1_e32 v191, v142
	v_cvt_f32_ubyte1_e32 v181, v143
	v_cvt_f32_ubyte3_e32 v193, v142
	v_cvt_f32_ubyte2_e32 v192, v142
	v_cvt_f32_ubyte3_e32 v185, v143
	v_cvt_f32_ubyte2_e32 v184, v143
	v_cvt_f32_ubyte0_e32 v180, v143
	v_lshl_add_u64 v[160:161], s[12:13], 0, v[144:145]
	s_cbranch_vccnz .LBB0_1179
	s_mov_b32 s26, 0x3b000000
	v_mov_b64_e32 v[142:143], s[26:27]
	s_mov_b32 s26, 0x3b800000
	v_pk_fma_f32 v[144:145], v[190:191], s[26:27], v[142:143] op_sel_hi:[1,0,0]
	v_pk_fma_f32 v[146:147], v[180:181], s[26:27], v[142:143] op_sel_hi:[1,0,0]
	v_pk_fma_f32 v[148:149], v[192:193], s[26:27], v[142:143] op_sel_hi:[1,0,0]
	v_pk_fma_f32 v[142:143], v[184:185], s[26:27], v[142:143] op_sel_hi:[1,0,0]
	v_pk_mul_f32 v[144:145], v[126:127], v[144:145]
	v_pk_mul_f32 v[146:147], v[122:123], v[146:147]
	v_pk_mul_f32 v[148:149], v[128:129], v[148:149]
	v_pk_mul_f32 v[182:183], v[124:125], v[142:143]
	v_cvt_pk_bf16_f32 v142, v144, v145
	v_cvt_pk_bf16_f32 v143, v148, v149
	v_cvt_pk_bf16_f32 v144, v146, v147
	v_cvt_pk_bf16_f32 v145, v182, v183
	v_lshl_add_u64 v[146:147], v[158:159], 1, v[160:161]
	s_mov_b64 s[28:29], 0
	global_store_dwordx4 v[146:147], v[142:145], off

.LBB0_1181:
	v_add_co_u32_e32 v122, vcc, 0x24000, v178
	v_mov_b32_e32 v183, 0
	s_nop 0
	v_addc_co_u32_e32 v123, vcc, 0, v179, vcc
	global_load_dwordx2 v[184:185], v[122:123], off offset:128
	s_and_b64 vcc, exec, s[8:9]
	v_mov_b32_e32 v207, 0
	v_mov_b32_e32 v203, 0
	v_mov_b32_e32 v182, 0
	s_cbranch_vccnz .LBB0_1183
	v_add_co_u32_e32 v122, vcc, 0x24000, v178
	s_nop 1
	v_addc_co_u32_e32 v123, vcc, 0, v179, vcc
	global_load_dwordx2 v[182:183], v[122:123], off offset:1152

.LBB0_1187:
	v_add_co_u32_e32 v114, vcc, 0x60000, v178
	v_mov_b32_e32 v181, 0
	s_nop 0
	v_addc_co_u32_e32 v115, vcc, 0, v179, vcc
	global_load_dwordx2 v[118:119], v[114:115], off
	s_and_b64 vcc, exec, s[8:9]
	v_mov_b32_e32 v205, 0
	v_mov_b32_e32 v201, 0
	v_mov_b32_e32 v180, 0
	s_cbranch_vccnz .LBB0_1189
	v_add_co_u32_e32 v114, vcc, 0x60000, v178
	s_nop 1
	v_addc_co_u32_e32 v115, vcc, 0, v179, vcc
	global_load_dwordx2 v[180:181], v[114:115], off offset:1024

.LBB0_1193:
	v_add_co_u32_e32 v106, vcc, 0x60000, v178
	v_mov_b32_e32 v117, 0
	s_nop 0
	v_addc_co_u32_e32 v107, vcc, 0, v179, vcc
	global_load_dwordx2 v[120:121], v[106:107], off offset:128
	s_and_b64 vcc, exec, s[8:9]
	v_mov_b32_e32 v206, 0
	v_mov_b32_e32 v202, 0
	v_mov_b32_e32 v116, 0
	s_cbranch_vccnz .LBB0_1195
	v_add_co_u32_e32 v106, vcc, 0x60000, v178
	s_nop 1
	v_addc_co_u32_e32 v107, vcc, 0, v179, vcc
	global_load_dwordx2 v[116:117], v[106:107], off offset:1152

.LBB0_1199:
	v_add_co_u32_e32 v98, vcc, 0x6c000, v178
	v_mov_b32_e32 v115, 0
	s_nop 0
	v_addc_co_u32_e32 v99, vcc, 0, v179, vcc
	global_load_dwordx2 v[102:103], v[98:99], off
	s_and_b64 vcc, exec, s[8:9]
	v_mov_b32_e32 v209, 0
	v_mov_b32_e32 v208, 0
	v_mov_b32_e32 v114, 0
	s_cbranch_vccnz .LBB0_1201
	v_add_co_u32_e32 v98, vcc, 0x6c000, v178
	s_nop 1
	v_addc_co_u32_e32 v99, vcc, 0, v179, vcc
	global_load_dwordx2 v[114:115], v[98:99], off offset:1024

.LBB0_1211:
	v_add_co_u32_e32 v82, vcc, 0x78000, v178
	s_waitcnt vmcnt(5)
	v_mov_b32_e32 v101, 0
	v_addc_co_u32_e32 v83, vcc, 0, v179, vcc
	global_load_dwordx2 v[188:189], v[82:83], off
	s_and_b64 vcc, exec, s[8:9]
	v_mov_b32_e32 v195, 0
	v_mov_b32_e32 v194, 0
	v_mov_b32_e32 v100, 0
	s_cbranch_vccnz .LBB0_1213
	v_add_co_u32_e32 v82, vcc, 0x78000, v178
	s_nop 1
	v_addc_co_u32_e32 v83, vcc, 0, v179, vcc
	global_load_dwordx2 v[100:101], v[82:83], off offset:1024

; __device__ __forceinline__ unsigned cvt_pk_bf16(float lo, float hi) { const f32x2_cv v = {lo, hi}; const bf16x2_cv b = __builtin_convertvector(v, bf16x2_cv); return __builtin_bit_cast(unsigned, b); }
; __device__ __forceinline__ float gate_c(unsigned w, int j) { return (float)((w >> (8 * j)) & 0xffu) + 0.5f; }
; __device__ __forceinline__ float gate_dq(unsigned w, int j) { return (float)((w >> (8 * j)) & 0xffu) * 0.00390625f + 0.001953125f; }
; #define MG_LOAD(k_, s_) do { const int ai_ = (k_) >> 3, m_ = ((k_) >> 1) & 3, bj_ = (k_) & 1; const unsigned char* q_ = gt + (size_t)(ai_ * HALF + m_ * 16) * 3072 + bj_ * HALF; \
;             ga[s_] = *(const v2u*)q_; gb[s_] = nb < 2 ? *(const v2u*)(q_ + 1024) : (v2u){0u, 0u}; } while (0)
;     __device__ __forceinline__ void operator()(f32x4 (&acc)[2][2][4][2], const Unit& u, int wr, int wc, int fr, int fq) const {
;     ...
;         for (int k = 0; k < 16; ++k) { const int ai = k >> 3, m = (k >> 1) & 3, bj = k & 1, s = k % PD;
;             const v2u gw = ga[s], hw = gb[s];
;             asm volatile("" :: "v"(gw), "v"(hw));
;             if (k + PD < 16) MG_LOAD(k + PD, s);
;             f32x4 o0 = acc[ai][bj][m][0], o1 = acc[ai][bj][m][1];
;             if (nb < 2) {
; #pragma unroll
;                 for (int j = 0; j < 4; ++j) { o0[j] *= gate_c(gw.x, j) * __builtin_amdgcn_rcpf(gate_c(hw.x, j)); o1[j] *= gate_c(gw.y, j) * __builtin_amdgcn_rcpf(gate_c(hw.y, j)); }
;                 acc[ai][bj][m][0] = o0; acc[ai][bj][m][1] = o1;
;             } else {
; #pragma unroll
;                 for (int j = 0; j < 4; ++j) { o0[j] *= gate_dq(gw.x, j); o1[j] *= gate_dq(gw.y, j); }
;                 u32x4 w; w.x = cvt_pk_bf16(o0[0], o0[1]); w.y = cvt_pk_bf16(o0[2], o0[3]); w.z = cvt_pk_bf16(o1[0], o1[1]); w.w = cvt_pk_bf16(o1[2], o1[3]);
;                 *(u32x4*)(MM + (size_t)(row0 + ai * HALF + m * 16) * 1024 + col0 + bj * HALF) = w;
.LBB0_1215:
	s_waitcnt vmcnt(6)
	v_mov_b32_e32 v204, v176
	v_mov_b32_e32 v200, v177
	v_mov_b32_e32 v104, 0
	s_andn2_b64 vcc, exec, s[26:27]
	v_mov_b32_e32 v170, 0
	v_mov_b32_e32 v171, 0
	v_mov_b32_e32 v172, 0
	v_mov_b32_e32 v173, 0
	v_mov_b32_e32 v174, 0
	v_mov_b32_e32 v175, 0
	v_mov_b32_e32 v176, 0
	v_mov_b32_e32 v177, 0
	s_cbranch_vccnz .LBB0_1217
	v_cvt_f32_ubyte0_e32 v83, v204
	v_add_f32_e32 v83, 0.5, v83
	v_rcp_f32_e32 v170, v83
	v_cvt_f32_ubyte0_e32 v83, v200
	v_add_f32_e32 v83, 0.5, v83
	v_rcp_f32_e32 v174, v83
	v_cvt_f32_ubyte1_e32 v83, v204
	v_add_f32_e32 v83, 0.5, v83
	v_rcp_f32_e32 v171, v83
	v_cvt_f32_ubyte1_e32 v83, v200
	v_add_f32_e32 v83, 0.5, v83
	v_rcp_f32_e32 v175, v83
	v_cvt_f32_ubyte2_e32 v83, v204
	v_add_f32_e32 v83, 0.5, v83
	v_rcp_f32_e32 v172, v83
	v_cvt_f32_ubyte2_e32 v83, v200
	v_add_f32_e32 v83, 0.5, v83
	v_rcp_f32_e32 v176, v83
	v_cvt_f32_ubyte3_e32 v83, v204
	v_add_f32_e32 v83, 0.5, v83
	v_rcp_f32_e32 v173, v83
	v_pk_add_f32 v[190:191], v[190:191], 0.5 op_sel_hi:[1,0]
	v_pk_add_f32 v[88:89], v[88:89], 0.5 op_sel_hi:[1,0]
	s_nop 0
	v_pk_mul_f32 v[88:89], v[88:89], v[170:171]
	v_pk_mul_f32 v[170:171], v[190:191], v[172:173]
	s_nop 0
	v_pk_mul_f32 v[172:173], v[80:81], v[170:171]
	v_pk_mul_f32 v[170:171], v[78:79], v[88:89]
	v_cvt_f32_ubyte3_e32 v78, v200
	v_add_f32_e32 v78, 0.5, v78
	v_rcp_f32_e32 v177, v78
	v_pk_add_f32 v[78:79], v[86:87], 0.5 op_sel_hi:[1,0]
	v_pk_add_f32 v[80:81], v[84:85], 0.5 op_sel_hi:[1,0]
	v_pk_mul_f32 v[78:79], v[78:79], v[176:177]
	v_pk_mul_f32 v[80:81], v[80:81], v[174:175]
	v_pk_mul_f32 v[176:177], v[76:77], v[78:79]
	v_pk_mul_f32 v[174:175], v[74:75], v[80:81]
.LBB0_1217:
	v_add_co_u32_e32 v74, vcc, 0x78000, v178
	s_waitcnt vmcnt(5)
	v_mov_b32_e32 v105, 0
	v_addc_co_u32_e32 v75, vcc, 0, v179, vcc
	global_load_dwordx2 v[190:191], v[74:75], off offset:128
	s_and_b64 vcc, exec, s[8:9]
	v_mov_b32_e32 v204, 0
	v_mov_b32_e32 v200, 0
	v_mov_b32_e32 v104, 0
	s_cbranch_vccnz .LBB0_1219
	v_add_co_u32_e32 v74, vcc, 0x78000, v178
	s_nop 1
	v_addc_co_u32_e32 v75, vcc, 0, v179, vcc
	global_load_dwordx2 v[104:105], v[74:75], off offset:1152
.LBB0_1219:
	s_waitcnt vmcnt(6)
	v_mov_b32_e32 v207, v182
	v_mov_b32_e32 v203, v183
	v_cvt_f32_ubyte0_e32 v88, v184
	s_mov_b64 s[26:27], -1
	s_and_b64 vcc, exec, s[6:7]
	v_cvt_f32_ubyte1_e32 v89, v184
	v_cvt_f32_ubyte1_e32 v85, v185
	v_cvt_f32_ubyte3_e32 v193, v184
	v_cvt_f32_ubyte2_e32 v192, v184
	v_cvt_f32_ubyte3_e32 v87, v185
	v_cvt_f32_ubyte2_e32 v86, v185
	v_cvt_f32_ubyte0_e32 v84, v185
	s_cbranch_vccnz .LBB0_1221
	s_mov_b32 s26, 0x3b000000
	v_mov_b64_e32 v[74:75], s[26:27]
	s_mov_b32 s26, 0x3b800000
	v_pk_fma_f32 v[76:77], v[88:89], s[26:27], v[74:75] op_sel_hi:[1,0,0]
	v_pk_fma_f32 v[78:79], v[84:85], s[26:27], v[74:75] op_sel_hi:[1,0,0]
	v_pk_mul_f32 v[76:77], v[70:71], v[76:77]
	v_pk_mul_f32 v[78:79], v[66:67], v[78:79]
	v_pk_fma_f32 v[80:81], v[192:193], s[26:27], v[74:75] op_sel_hi:[1,0,0]
	v_pk_fma_f32 v[74:75], v[86:87], s[26:27], v[74:75] op_sel_hi:[1,0,0]
	v_ashrrev_i32_e32 v83, 31, v82
	v_pk_mul_f32 v[182:183], v[68:69], v[74:75]
	v_cvt_pk_bf16_f32 v74, v76, v77
	v_cvt_pk_bf16_f32 v76, v78, v79
	v_lshlrev_b64 v[78:79], 11, v[82:83]
	v_pk_mul_f32 v[80:81], v[72:73], v[80:81]
	v_lshl_add_u64 v[78:79], s[12:13], 0, v[78:79]
	v_cvt_pk_bf16_f32 v75, v80, v81
	v_cvt_pk_bf16_f32 v77, v182, v183
	v_lshl_add_u64 v[78:79], v[158:159], 1, v[78:79]
	s_mov_b64 s[26:27], 0
	global_store_dwordx4 v[78:79], v[74:77], off offset:256

; #define MG_LOAD(k_, s_) do { const int ai_ = (k_) >> 3, m_ = ((k_) >> 1) & 3, bj_ = (k_) & 1; const unsigned char* q_ = gt + (size_t)(ai_ * HALF + m_ * 16) * 3072 + bj_ * HALF; \
;             ga[s_] = *(const v2u*)q_; gb[s_] = nb < 2 ? *(const v2u*)(q_ + 1024) : (v2u){0u, 0u}; } while (0)
;     __device__ __forceinline__ void operator()(f32x4 (&acc)[2][2][4][2], const Unit& u, int wr, int wc, int fr, int fq) const {
;     ...
; #pragma unroll
;         for (int k = 0; k < PD; ++k) MG_LOAD(k, k);
; #pragma unroll
;         for (int k = 0; k < 16; ++k) { const int ai = k >> 3, m = (k >> 1) & 3, bj = k & 1, s = k % PD;
;             const v2u gw = ga[s], hw = gb[s];
;             asm volatile("" :: "v"(gw), "v"(hw));
;             if (k + PD < 16) MG_LOAD(k + PD, s);
.LBB0_1223:
	s_waitcnt vmcnt(5)
	v_mov_b32_e32 v205, v180
	v_mov_b32_e32 v201, v181
	v_add_co_u32_e32 v66, vcc, 0x84000, v178
	s_waitcnt vmcnt(5)
	v_mov_b32_e32 v183, 0
	v_addc_co_u32_e32 v67, vcc, 0, v179, vcc
	global_load_dwordx2 v[180:181], v[66:67], off
	s_and_b64 vcc, exec, s[8:9]
	v_mov_b32_e32 v185, 0
	v_mov_b32_e32 v184, 0
	v_mov_b32_e32 v182, 0
	s_cbranch_vccnz .LBB0_1225
	v_add_co_u32_e32 v66, vcc, 0x84000, v178
	s_nop 1
	v_addc_co_u32_e32 v67, vcc, 0, v179, vcc
	global_load_dwordx2 v[182:183], v[66:67], off offset:1024

; #define MG_LOAD(k_, s_) do { const int ai_ = (k_) >> 3, m_ = ((k_) >> 1) & 3, bj_ = (k_) & 1; const unsigned char* q_ = gt + (size_t)(ai_ * HALF + m_ * 16) * 3072 + bj_ * HALF; \
;             ga[s_] = *(const v2u*)q_; gb[s_] = nb < 2 ? *(const v2u*)(q_ + 1024) : (v2u){0u, 0u}; } while (0)
;     __device__ __forceinline__ void operator()(f32x4 (&acc)[2][2][4][2], const Unit& u, int wr, int wc, int fr, int fq) const {
;     ...
; #pragma unroll
;         for (int k = 0; k < PD; ++k) MG_LOAD(k, k);
; #pragma unroll
;         for (int k = 0; k < 16; ++k) { const int ai = k >> 3, m = (k >> 1) & 3, bj = k & 1, s = k % PD;
;             const v2u gw = ga[s], hw = gb[s];
;             asm volatile("" :: "v"(gw), "v"(hw));
;             if (k + PD < 16) MG_LOAD(k + PD, s);
.LBB0_1229:
	s_waitcnt vmcnt(5)
	v_mov_b32_e32 v206, v116
	v_mov_b32_e32 v202, v117
	v_add_co_u32_e32 v58, vcc, 0x84000, v178
	s_waitcnt vmcnt(5)
	v_mov_b32_e32 v119, 0
	v_addc_co_u32_e32 v59, vcc, 0, v179, vcc
	global_load_dwordx2 v[116:117], v[58:59], off offset:128
	s_and_b64 vcc, exec, s[8:9]
	v_mov_b32_e32 v193, 0
	v_mov_b32_e32 v192, 0
	v_mov_b32_e32 v118, 0
	s_cbranch_vccnz .LBB0_1231
	v_add_co_u32_e32 v58, vcc, 0x84000, v178
	s_nop 1
	v_addc_co_u32_e32 v59, vcc, 0, v179, vcc
	global_load_dwordx2 v[118:119], v[58:59], off offset:1152

; __device__ __forceinline__ float gate_c(unsigned w, int j) { return (float)((w >> (8 * j)) & 0xffu) + 0.5f; }
; #define MG_LOAD(k_, s_) do { const int ai_ = (k_) >> 3, m_ = ((k_) >> 1) & 3, bj_ = (k_) & 1; const unsigned char* q_ = gt + (size_t)(ai_ * HALF + m_ * 16) * 3072 + bj_ * HALF; \
;             ga[s_] = *(const v2u*)q_; gb[s_] = nb < 2 ? *(const v2u*)(q_ + 1024) : (v2u){0u, 0u}; } while (0)
;     __device__ __forceinline__ void operator()(f32x4 (&acc)[2][2][4][2], const Unit& u, int wr, int wc, int fr, int fq) const {
;     ...
;             const v2u gw = ga[s], hw = gb[s];
;             asm volatile("" :: "v"(gw), "v"(hw));
;             if (k + PD < 16) MG_LOAD(k + PD, s);
;             f32x4 o0 = acc[ai][bj][m][0], o1 = acc[ai][bj][m][1];
;             if (nb < 2) {
; #pragma unroll
;                 for (int j = 0; j < 4; ++j) { o0[j] *= gate_c(gw.x, j) * __builtin_amdgcn_rcpf(gate_c(hw.x, j)); o1[j] *= gate_c(gw.y, j) * __builtin_amdgcn_rcpf(gate_c(hw.y, j)); }
;                 acc[ai][bj][m][0] = o0; acc[ai][bj][m][1] = o1;
.LBB0_1237:
	s_waitcnt vmcnt(5)
	v_mov_b32_e32 v209, v114
	v_mov_b32_e32 v208, v115
	s_nop 1
	v_mov_b32_e32 v82, 0
	s_andn2_b64 vcc, exec, s[8:9]
	v_mov_b32_e32 v83, 0
	v_mov_b32_e32 v84, 0
	v_mov_b32_e32 v85, 0
	v_mov_b32_e32 v86, 0
	v_mov_b32_e32 v87, 0
	v_mov_b32_e32 v88, 0
	v_mov_b32_e32 v89, 0
	s_cbranch_vccnz .LBB0_1239
	v_cvt_f32_ubyte0_e32 v83, v208
	v_add_f32_e32 v83, 0.5, v83
	v_cvt_f32_ubyte0_e32 v82, v209
	v_rcp_f32_e32 v86, v83
	v_cvt_f32_ubyte1_e32 v83, v209
	v_add_f32_e32 v82, 0.5, v82
	v_add_f32_e32 v83, 0.5, v83
	v_rcp_f32_e32 v82, v82
	v_rcp_f32_e32 v83, v83
	v_cvt_f32_ubyte1_e32 v84, v208
	v_cvt_f32_ubyte2_e32 v85, v208
	v_add_f32_e32 v84, 0.5, v84
	v_add_f32_e32 v85, 0.5, v85
	v_rcp_f32_e32 v87, v84
	v_cvt_f32_ubyte2_e32 v84, v209
	v_rcp_f32_e32 v88, v85
	v_cvt_f32_ubyte3_e32 v85, v209
	v_pk_add_f32 v[54:55], v[54:55], 0.5 op_sel_hi:[1,0]
	v_add_f32_e32 v84, 0.5, v84
	v_add_f32_e32 v85, 0.5, v85
	v_pk_mul_f32 v[54:55], v[54:55], v[82:83]
	v_rcp_f32_e32 v84, v84
	v_rcp_f32_e32 v85, v85
	v_pk_mul_f32 v[82:83], v[46:47], v[54:55]
	v_cvt_f32_ubyte3_e32 v46, v208
	v_add_f32_e32 v46, 0.5, v46
	v_rcp_f32_e32 v89, v46
	v_pk_add_f32 v[56:57], v[56:57], 0.5 op_sel_hi:[1,0]
	v_pk_add_f32 v[46:47], v[52:53], 0.5 op_sel_hi:[1,0]
	v_pk_mul_f32 v[56:57], v[56:57], v[84:85]
	v_pk_mul_f32 v[46:47], v[46:47], v[88:89]
	v_pk_mul_f32 v[84:85], v[48:49], v[56:57]
	v_pk_add_f32 v[48:49], v[50:51], 0.5 op_sel_hi:[1,0]
	v_pk_mul_f32 v[88:89], v[44:45], v[46:47]
	v_pk_mul_f32 v[48:49], v[48:49], v[86:87]
	s_nop 0
	v_pk_mul_f32 v[86:87], v[42:43], v[48:49]

; __device__ __forceinline__ float gate_c(unsigned w, int j) { return (float)((w >> (8 * j)) & 0xffu) + 0.5f; }
; #define MG_LOAD(k_, s_) do { const int ai_ = (k_) >> 3, m_ = ((k_) >> 1) & 3, bj_ = (k_) & 1; const unsigned char* q_ = gt + (size_t)(ai_ * HALF + m_ * 16) * 3072 + bj_ * HALF; \
;             ga[s_] = *(const v2u*)q_; gb[s_] = nb < 2 ? *(const v2u*)(q_ + 1024) : (v2u){0u, 0u}; } while (0)
;     __device__ __forceinline__ void operator()(f32x4 (&acc)[2][2][4][2], const Unit& u, int wr, int wc, int fr, int fq) const {
;     ...
;             const v2u gw = ga[s], hw = gb[s];
;             asm volatile("" :: "v"(gw), "v"(hw));
;             if (k + PD < 16) MG_LOAD(k + PD, s);
;             f32x4 o0 = acc[ai][bj][m][0], o1 = acc[ai][bj][m][1];
;             if (nb < 2) {
; #pragma unroll
;                 for (int j = 0; j < 4; ++j) { o0[j] *= gate_c(gw.x, j) * __builtin_amdgcn_rcpf(gate_c(hw.x, j)); o1[j] *= gate_c(gw.y, j) * __builtin_amdgcn_rcpf(gate_c(hw.y, j)); }
;                 acc[ai][bj][m][0] = o0; acc[ai][bj][m][1] = o1;
.LBB0_1245:
	s_waitcnt vmcnt(3)
	v_mov_b32_e32 v195, v100
	v_mov_b32_e32 v194, v101
	v_mov_b32_e32 v98, 0
	s_andn2_b64 vcc, exec, s[8:9]
	v_mov_b32_e32 v99, 0
	v_mov_b32_e32 v100, 0
	v_mov_b32_e32 v101, 0
	v_mov_b32_e32 v102, 0
	v_mov_b32_e32 v103, 0
	v_mov_b32_e32 v114, 0
	v_mov_b32_e32 v115, 0
	s_cbranch_vccnz .LBB0_1247
	v_cvt_f32_ubyte0_e32 v51, v194
	v_add_f32_e32 v51, 0.5, v51
	v_cvt_f32_ubyte0_e32 v50, v195
	v_rcp_f32_e32 v52, v51
	v_cvt_f32_ubyte1_e32 v51, v195
	v_add_f32_e32 v50, 0.5, v50
	v_add_f32_e32 v51, 0.5, v51
	v_rcp_f32_e32 v50, v50
	v_rcp_f32_e32 v51, v51
	v_cvt_f32_ubyte2_e32 v55, v194
	v_add_f32_e32 v55, 0.5, v55
	v_cvt_f32_ubyte2_e32 v54, v195
	v_rcp_f32_e32 v56, v55
	v_cvt_f32_ubyte3_e32 v55, v195
	v_pk_add_f32 v[38:39], v[38:39], 0.5 op_sel_hi:[1,0]
	v_add_f32_e32 v54, 0.5, v54
	v_add_f32_e32 v55, 0.5, v55
	v_pk_mul_f32 v[38:39], v[38:39], v[50:51]
	v_cvt_f32_ubyte1_e32 v53, v194
	v_rcp_f32_e32 v54, v54
	v_rcp_f32_e32 v55, v55
	v_pk_mul_f32 v[98:99], v[30:31], v[38:39]
	v_cvt_f32_ubyte3_e32 v30, v194
	v_add_f32_e32 v53, 0.5, v53
	v_add_f32_e32 v30, 0.5, v30
	v_rcp_f32_e32 v53, v53
	v_rcp_f32_e32 v57, v30
	v_pk_add_f32 v[40:41], v[40:41], 0.5 op_sel_hi:[1,0]
	v_pk_add_f32 v[30:31], v[36:37], 0.5 op_sel_hi:[1,0]
	v_pk_mul_f32 v[40:41], v[40:41], v[54:55]
	v_pk_mul_f32 v[30:31], v[30:31], v[56:57]
	v_pk_mul_f32 v[100:101], v[32:33], v[40:41]
	v_pk_add_f32 v[32:33], v[34:35], 0.5 op_sel_hi:[1,0]
	v_pk_mul_f32 v[114:115], v[28:29], v[30:31]
	v_pk_mul_f32 v[32:33], v[32:33], v[52:53]
	s_nop 0
	v_pk_mul_f32 v[102:103], v[26:27], v[32:33]

; __device__ __forceinline__ float gate_c(unsigned w, int j) { return (float)((w >> (8 * j)) & 0xffu) + 0.5f; }
; #define MG_LOAD(k_, s_) do { const int ai_ = (k_) >> 3, m_ = ((k_) >> 1) & 3, bj_ = (k_) & 1; const unsigned char* q_ = gt + (size_t)(ai_ * HALF + m_ * 16) * 3072 + bj_ * HALF; \
;             ga[s_] = *(const v2u*)q_; gb[s_] = nb < 2 ? *(const v2u*)(q_ + 1024) : (v2u){0u, 0u}; } while (0)
;     __device__ __forceinline__ void operator()(f32x4 (&acc)[2][2][4][2], const Unit& u, int wr, int wc, int fr, int fq) const {
;     ...
;             const v2u gw = ga[s], hw = gb[s];
;             asm volatile("" :: "v"(gw), "v"(hw));
;             if (k + PD < 16) MG_LOAD(k + PD, s);
;             f32x4 o0 = acc[ai][bj][m][0], o1 = acc[ai][bj][m][1];
;             if (nb < 2) {
; #pragma unroll
;                 for (int j = 0; j < 4; ++j) { o0[j] *= gate_c(gw.x, j) * __builtin_amdgcn_rcpf(gate_c(hw.x, j)); o1[j] *= gate_c(gw.y, j) * __builtin_amdgcn_rcpf(gate_c(hw.y, j)); }
;                 acc[ai][bj][m][0] = o0; acc[ai][bj][m][1] = o1;
.LBB0_1249:
	s_waitcnt vmcnt(2)
	v_mov_b32_e32 v204, v104
	v_mov_b32_e32 v200, v105
	s_nop 1
	v_mov_b32_e32 v26, 0
	s_andn2_b64 vcc, exec, s[8:9]
	v_mov_b32_e32 v27, 0
	v_mov_b32_e32 v28, 0
	v_mov_b32_e32 v29, 0
	v_mov_b32_e32 v30, 0
	v_mov_b32_e32 v31, 0
	v_mov_b32_e32 v32, 0
	v_mov_b32_e32 v33, 0
	s_cbranch_vccnz .LBB0_1251
	v_cvt_f32_ubyte0_e32 v27, v200
	v_add_f32_e32 v27, 0.5, v27
	v_cvt_f32_ubyte0_e32 v26, v204
	v_rcp_f32_e32 v30, v27
	v_cvt_f32_ubyte1_e32 v27, v204
	v_add_f32_e32 v26, 0.5, v26
	v_add_f32_e32 v27, 0.5, v27
	v_rcp_f32_e32 v26, v26
	v_rcp_f32_e32 v27, v27
	v_cvt_f32_ubyte1_e32 v28, v200
	v_cvt_f32_ubyte2_e32 v29, v200
	v_add_f32_e32 v28, 0.5, v28
	v_add_f32_e32 v29, 0.5, v29
	v_rcp_f32_e32 v31, v28
	v_cvt_f32_ubyte2_e32 v28, v204
	v_rcp_f32_e32 v32, v29
	v_cvt_f32_ubyte3_e32 v29, v204
	v_pk_add_f32 v[38:39], v[38:39], 0.5 op_sel_hi:[1,0]
	v_add_f32_e32 v28, 0.5, v28
	v_add_f32_e32 v29, 0.5, v29
	v_pk_mul_f32 v[26:27], v[38:39], v[26:27]
	v_rcp_f32_e32 v28, v28
	v_rcp_f32_e32 v29, v29
	v_pk_mul_f32 v[26:27], v[22:23], v[26:27]
	v_cvt_f32_ubyte3_e32 v22, v200
	v_add_f32_e32 v22, 0.5, v22
	v_rcp_f32_e32 v33, v22
	v_pk_add_f32 v[40:41], v[40:41], 0.5 op_sel_hi:[1,0]
	v_pk_add_f32 v[22:23], v[36:37], 0.5 op_sel_hi:[1,0]
	v_pk_mul_f32 v[28:29], v[40:41], v[28:29]
	v_pk_mul_f32 v[22:23], v[22:23], v[32:33]
	v_pk_mul_f32 v[28:29], v[24:25], v[28:29]
	v_pk_add_f32 v[24:25], v[34:35], 0.5 op_sel_hi:[1,0]
	v_pk_mul_f32 v[32:33], v[20:21], v[22:23]
	v_pk_mul_f32 v[24:25], v[24:25], v[30:31]
	s_nop 0
	v_pk_mul_f32 v[30:31], v[18:19], v[24:25]

; __device__ __forceinline__ float gate_c(unsigned w, int j) { return (float)((w >> (8 * j)) & 0xffu) + 0.5f; }
; #define MG_LOAD(k_, s_) do { const int ai_ = (k_) >> 3, m_ = ((k_) >> 1) & 3, bj_ = (k_) & 1; const unsigned char* q_ = gt + (size_t)(ai_ * HALF + m_ * 16) * 3072 + bj_ * HALF; \
;             ga[s_] = *(const v2u*)q_; gb[s_] = nb < 2 ? *(const v2u*)(q_ + 1024) : (v2u){0u, 0u}; } while (0)
;     __device__ __forceinline__ void operator()(f32x4 (&acc)[2][2][4][2], const Unit& u, int wr, int wc, int fr, int fq) const {
;     ...
;             const v2u gw = ga[s], hw = gb[s];
;             asm volatile("" :: "v"(gw), "v"(hw));
;             if (k + PD < 16) MG_LOAD(k + PD, s);
;             f32x4 o0 = acc[ai][bj][m][0], o1 = acc[ai][bj][m][1];
;             if (nb < 2) {
; #pragma unroll
;                 for (int j = 0; j < 4; ++j) { o0[j] *= gate_c(gw.x, j) * __builtin_amdgcn_rcpf(gate_c(hw.x, j)); o1[j] *= gate_c(gw.y, j) * __builtin_amdgcn_rcpf(gate_c(hw.y, j)); }
;                 acc[ai][bj][m][0] = o0; acc[ai][bj][m][1] = o1;
.LBB0_1253:
	s_waitcnt vmcnt(1)
	v_mov_b32_e32 v185, v182
	v_mov_b32_e32 v184, v183
	v_mov_b32_e32 v104, 0
	s_andn2_b64 vcc, exec, s[8:9]
	v_mov_b32_e32 v105, 0
	v_mov_b32_e32 v120, 0
	v_mov_b32_e32 v121, 0
	v_mov_b32_e32 v178, 0
	v_mov_b32_e32 v179, 0
	v_mov_b32_e32 v180, 0
	v_mov_b32_e32 v181, 0
	s_cbranch_vccnz .LBB0_1255
	v_cvt_f32_ubyte0_e32 v35, v184
	v_add_f32_e32 v35, 0.5, v35
	v_cvt_f32_ubyte0_e32 v34, v185
	v_rcp_f32_e32 v36, v35
	v_cvt_f32_ubyte1_e32 v35, v185
	v_add_f32_e32 v34, 0.5, v34
	v_add_f32_e32 v35, 0.5, v35
	v_rcp_f32_e32 v34, v34
	v_rcp_f32_e32 v35, v35
	v_cvt_f32_ubyte2_e32 v39, v184
	v_add_f32_e32 v39, 0.5, v39
	v_cvt_f32_ubyte2_e32 v38, v185
	v_rcp_f32_e32 v40, v39
	v_cvt_f32_ubyte3_e32 v39, v185
	v_pk_add_f32 v[22:23], v[22:23], 0.5 op_sel_hi:[1,0]
	v_add_f32_e32 v38, 0.5, v38
	v_add_f32_e32 v39, 0.5, v39
	v_pk_mul_f32 v[22:23], v[22:23], v[34:35]
	v_cvt_f32_ubyte1_e32 v37, v184
	v_rcp_f32_e32 v38, v38
	v_rcp_f32_e32 v39, v39
	v_pk_mul_f32 v[104:105], v[14:15], v[22:23]
	v_cvt_f32_ubyte3_e32 v14, v184
	v_add_f32_e32 v37, 0.5, v37
	v_add_f32_e32 v14, 0.5, v14
	v_rcp_f32_e32 v37, v37
	v_rcp_f32_e32 v41, v14
	v_pk_add_f32 v[24:25], v[24:25], 0.5 op_sel_hi:[1,0]
	v_pk_add_f32 v[14:15], v[20:21], 0.5 op_sel_hi:[1,0]
	v_pk_mul_f32 v[24:25], v[24:25], v[38:39]
	v_pk_mul_f32 v[14:15], v[14:15], v[40:41]
	v_pk_mul_f32 v[120:121], v[16:17], v[24:25]
	v_pk_add_f32 v[16:17], v[18:19], 0.5 op_sel_hi:[1,0]
	v_pk_mul_f32 v[180:181], v[12:13], v[14:15]
	v_pk_mul_f32 v[16:17], v[16:17], v[36:37]
	s_nop 0
	v_pk_mul_f32 v[178:179], v[10:11], v[16:17]

; __device__ __forceinline__ float gate_c(unsigned w, int j) { return (float)((w >> (8 * j)) & 0xffu) + 0.5f; }
; #define MG_LOAD(k_, s_) do { const int ai_ = (k_) >> 3, m_ = ((k_) >> 1) & 3, bj_ = (k_) & 1; const unsigned char* q_ = gt + (size_t)(ai_ * HALF + m_ * 16) * 3072 + bj_ * HALF; \
;             ga[s_] = *(const v2u*)q_; gb[s_] = nb < 2 ? *(const v2u*)(q_ + 1024) : (v2u){0u, 0u}; } while (0)
;     __device__ __forceinline__ void operator()(f32x4 (&acc)[2][2][4][2], const Unit& u, int wr, int wc, int fr, int fq) const {
;     ...
;             const v2u gw = ga[s], hw = gb[s];
;             asm volatile("" :: "v"(gw), "v"(hw));
;             if (k + PD < 16) MG_LOAD(k + PD, s);
;             f32x4 o0 = acc[ai][bj][m][0], o1 = acc[ai][bj][m][1];
;             if (nb < 2) {
; #pragma unroll
;                 for (int j = 0; j < 4; ++j) { o0[j] *= gate_c(gw.x, j) * __builtin_amdgcn_rcpf(gate_c(hw.x, j)); o1[j] *= gate_c(gw.y, j) * __builtin_amdgcn_rcpf(gate_c(hw.y, j)); }
;                 acc[ai][bj][m][0] = o0; acc[ai][bj][m][1] = o1;
.LBB0_1257:
	s_waitcnt vmcnt(0)
	v_mov_b32_e32 v193, v118
	v_mov_b32_e32 v192, v119
	s_nop 1
	v_mov_b32_e32 v10, 0
	s_andn2_b64 vcc, exec, s[8:9]
	v_mov_b32_e32 v11, 0
	v_mov_b32_e32 v12, 0
	v_mov_b32_e32 v13, 0
	v_mov_b32_e32 v14, 0
	v_mov_b32_e32 v15, 0
	v_mov_b32_e32 v16, 0
	v_mov_b32_e32 v17, 0
	s_cbranch_vccnz .LBB0_1259
	v_cvt_f32_ubyte0_e32 v11, v192
	v_add_f32_e32 v11, 0.5, v11
	v_cvt_f32_ubyte0_e32 v10, v193
	v_rcp_f32_e32 v14, v11
	v_cvt_f32_ubyte1_e32 v11, v193
	v_add_f32_e32 v10, 0.5, v10
	v_add_f32_e32 v11, 0.5, v11
	v_rcp_f32_e32 v10, v10
	v_rcp_f32_e32 v11, v11
	v_cvt_f32_ubyte1_e32 v12, v192
	v_cvt_f32_ubyte2_e32 v13, v192
	v_add_f32_e32 v12, 0.5, v12
	v_add_f32_e32 v13, 0.5, v13
	v_rcp_f32_e32 v15, v12
	v_cvt_f32_ubyte2_e32 v12, v193
	v_rcp_f32_e32 v16, v13
	v_cvt_f32_ubyte3_e32 v13, v193
	v_pk_add_f32 v[22:23], v[22:23], 0.5 op_sel_hi:[1,0]
	v_add_f32_e32 v12, 0.5, v12
	v_add_f32_e32 v13, 0.5, v13
	v_pk_mul_f32 v[10:11], v[22:23], v[10:11]
	v_rcp_f32_e32 v12, v12
	v_rcp_f32_e32 v13, v13
	v_pk_mul_f32 v[10:11], v[6:7], v[10:11]
	v_cvt_f32_ubyte3_e32 v6, v192
	v_add_f32_e32 v6, 0.5, v6
	v_rcp_f32_e32 v17, v6
	v_pk_add_f32 v[24:25], v[24:25], 0.5 op_sel_hi:[1,0]
	v_pk_add_f32 v[6:7], v[20:21], 0.5 op_sel_hi:[1,0]
	v_pk_mul_f32 v[12:13], v[24:25], v[12:13]
	v_pk_mul_f32 v[6:7], v[6:7], v[16:17]
	v_pk_mul_f32 v[12:13], v[8:9], v[12:13]
	v_pk_add_f32 v[8:9], v[18:19], 0.5 op_sel_hi:[1,0]
	v_pk_mul_f32 v[16:17], v[4:5], v[6:7]
	v_pk_mul_f32 v[8:9], v[8:9], v[14:15]
	s_nop 0
	v_pk_mul_f32 v[14:15], v[2:3], v[8:9]
